# attention phase: one static s_setprio 1 for waves 4-7 (younger half), reset at phase end
# speedup vs baseline: 1.0129x; 1.0089x over previous
.LBB0_667:
	v_writelane_b32 v255, s94, 2
	v_writelane_b32 v254, s72, 50
	s_andn2_b64 vcc, exec, s[8:9]
	v_writelane_b32 v255, s95, 3
	v_writelane_b32 v254, s73, 51
	v_writelane_b32 v255, s62, 4
	v_writelane_b32 v254, s74, 52
	v_writelane_b32 v254, s75, 53
	v_writelane_b32 v255, s63, 5
	s_cbranch_vccnz .LBB0_736
	s_bfe_u32 s4, s34, 0x30002
	s_add_i32 s5, s4, 1
	v_cvt_f32_ubyte0_e32 v0, s5
	s_mov_b32 s5, 0x42fc0000
	s_waitcnt vmcnt(0)
	v_ashrrev_i32_e32 v5, 6, v166
	v_and_b32_e32 v107, 15, v166
	s_ashr_i32 s8, s34, 5
	v_cmp_lt_f32_e32 vcc, s5, v0
	v_mov_b32_e32 v2, 0x42800000
	s_and_b32 s20, s34, 3
	s_ashr_i32 s9, s8, 31
	v_cndmask_b32_e32 v2, 0, v2, vcc
	v_lshl_or_b32 v109, v5, 4, v107
	s_lshl_b64 s[18:19], s[8:9], 12
	v_sub_f32_e32 v0, v2, v0
	v_lshl_add_u32 v2, s20, 10, v109
	v_exp_f32_e32 v0, v0
	s_and_b64 s[8:9], vcc, exec
	v_ashrrev_i32_e32 v3, 31, v2
	v_lshl_add_u64 v[2:3], s[18:19], 0, v[2:3]
	v_readlane_b32 s8, v253, 53
	v_lshlrev_b64 v[2:3], 11, v[2:3]
	v_readlane_b32 s9, v253, 54
	v_bfe_u32 v6, v166, 4, 2
	s_cselect_b32 s5, 0xffffffc0, 0
	v_lshl_add_u64 v[2:3], s[8:9], 0, v[2:3]
	s_lshl_b32 s6, s4, 8
	v_ldexp_f32 v7, v0, s5
	v_lshl_add_u64 v[2:3], v[2:3], 0, s[6:7]
	v_lshlrev_b32_e32 v0, 4, v6
	v_lshl_add_u64 v[2:3], v[2:3], 0, v[0:1]
	global_load_dwordx4 v[62:65], v[2:3], off
	global_load_dwordx4 v[58:61], v[2:3], off offset:64
	global_load_dwordx4 v[54:57], v[2:3], off offset:128
	global_load_dwordx4 v[50:53], v[2:3], off offset:192
	v_and_b32_e32 v3, 1, v5
	v_cmp_eq_u32_e64 s[8:9], 0, v3
	s_lshl_b32 s6, s20, 3
	v_writelane_b32 v255, s6, 6
	v_writelane_b32 v254, s8, 54
	v_and_b32_e32 v14, 64, v224
	v_writelane_b32 v255, s20, 7
	v_writelane_b32 v254, s9, 55
	v_cmp_eq_u32_e64 s[8:9], 1, v3
	v_xor_b32_e32 v13, 16, v224
	v_add_u32_e32 v14, 64, v14
	v_writelane_b32 v254, s8, 62
	v_and_b32_e32 v111, -2, v5
	v_cmp_lt_i32_e32 vcc, v13, v14
	v_writelane_b32 v254, s9, 63
	s_lshl_b32 s8, s20, 2
	v_writelane_b32 v255, s8, 8
	v_cmp_eq_u32_e64 s[8:9], 0, v6
	v_add_u32_e32 v106, 0, v0
	v_lshl_or_b32 v0, v3, 4, v107
	v_writelane_b32 v254, s8, 60
	v_cndmask_b32_e32 v13, v224, v13, vcc
	v_or_b32_e32 v3, 0x80, v0
	v_writelane_b32 v254, s9, 61
	v_cmp_lt_i32_e64 s[8:9], 7, v111
	v_lshlrev_b32_e32 v8, 2, v6
	v_lshlrev_b32_e32 v116, 2, v13
	v_xor_b32_e32 v13, 32, v224
	v_writelane_b32 v254, s8, 56
	v_sub_u32_e32 v9, v3, v8
	v_cmp_lt_i32_e32 vcc, v13, v14
	v_lshlrev_b32_e32 v14, 4, v166
	v_writelane_b32 v254, s9, 57
	s_movk_i32 s8, 0x81
	v_lshlrev_b32_e32 v4, 3, v6
	v_and_b32_e32 v15, 48, v14
	v_readlane_b32 s6, v253, 20
	v_and_b32_e32 v14, 0xf0, v14
	v_subrev_co_u32_e64 v6, s[20:21], s8, v9
	v_add_u32_e32 v108, s6, v15
	v_add_u32_e32 v123, s6, v14
	v_writelane_b32 v254, s20, 58
	v_sub_u32_e32 v3, v8, v3
	s_movk_i32 s6, 0xff7e
	v_writelane_b32 v254, s21, 59
	v_cmp_lt_u32_e64 s[20:21], s6, v3
	v_add_u32_e32 v3, -2, v9
	v_mul_f32_e32 v2, 0x3fb8aa3b, v7
	v_writelane_b32 v255, s20, 9
	v_cvt_f32_ubyte0_e32 v10, v9
	v_mul_f32_e32 v11, 0x41800000, v2
	v_writelane_b32 v255, s21, 10
	v_cmp_gt_u32_e64 s[20:21], s8, v3
	v_add_u32_e32 v3, -3, v9
	v_mul_f32_e32 v12, v2, v10
	v_writelane_b32 v255, s20, 11
	s_mov_b32 s6, 0x40400000
	v_sub_u32_e32 v0, v0, v8
	v_writelane_b32 v255, s21, 12
	v_cmp_gt_u32_e64 s[20:21], s8, v3
	v_fma_f32 v145, v11, s6, -v12
	s_mov_b32 s6, 0x40a00000
	v_writelane_b32 v255, s20, 13
	v_lshlrev_b32_e32 v15, 3, v166
	v_fma_f32 v153, v11, s6, -v12
	v_writelane_b32 v255, s21, 14
	v_cmp_gt_u32_e64 s[20:21], s8, v0
	v_add_u32_e32 v0, 0xffffff7e, v9
	s_mov_b32 s6, 0x40c00000
	v_cmp_gt_u32_e64 s[42:43], s8, v0
	v_add_u32_e32 v0, 0xffffff7d, v9
	s_lshl_b32 s5, s4, 7
	v_and_b32_e32 v15, 0x78, v15
	v_add_u32_e32 v3, -16, v9
	v_fma_f32 v157, v11, s6, -v12
	s_mov_b32 s6, 0x40e00000
	v_cmp_gt_u32_e64 s[44:45], s8, v0
	v_add_u32_e32 v0, 0xffffff70, v9
	v_or_b32_e32 v110, s5, v15
	v_add_u32_e32 v15, 0x200, v166
	v_cmp_gt_u32_e64 s[58:59], s8, v3
	v_subrev_u32_e32 v3, 17, v9
	v_fma_f32 v161, v11, s6, -v12
	s_mov_b32 s6, 0x41000000
	v_cmp_gt_u32_e64 s[48:49], s8, v0
	v_add_u32_e32 v0, 0xffffff6f, v9
	v_cndmask_b32_e32 v13, v224, v13, vcc
	v_ashrrev_i32_e32 v119, 4, v15
	v_add_u32_e32 v15, 0x400, v166
	v_cmp_gt_u32_e64 s[60:61], s8, v3
	v_subrev_u32_e32 v3, 18, v9
	v_fma_f32 v169, v11, s6, -v12
	s_mov_b32 s6, 0x41100000
	v_cmp_gt_u32_e64 s[50:51], s8, v0
	v_add_u32_e32 v0, 0xffffff6e, v9
	v_lshlrev_b32_e32 v117, 2, v13
	v_bfe_u32 v13, v166, 2, 2
	v_ashrrev_i32_e32 v120, 4, v15
	v_add_u32_e32 v15, 0x600, v166
	v_fma_f32 v133, v11, 0, -v12
	v_fma_f32 v137, -v2, v10, v11
	v_cmp_gt_u32_e64 s[62:63], s8, v3
	v_subrev_u32_e32 v3, 19, v9
	v_fma_f32 v141, v11, 2.0, -v12
	v_fma_f32 v149, v11, 4.0, -v12
	v_fma_f32 v173, v11, s6, -v12
	v_cmp_gt_u32_e64 s[90:91], s8, v0
	v_add_u32_e32 v0, 0xffffff6d, v9
	s_mov_b32 s53, 0
	v_ashrrev_i32_e32 v118, 4, v166
	v_ashrrev_i32_e32 v121, 4, v15
	v_add_u32_e32 v122, 0, v14
	v_or_b32_e32 v124, 1, v5
	v_add_u32_e32 v125, 2, v111
	v_add_u32_e32 v126, 3, v111
	v_add_u32_e32 v127, 4, v111
	v_add_u32_e32 v128, 5, v111
	v_add_u32_e32 v129, 6, v111
	v_add_u32_e32 v130, 7, v111
	v_add_u32_e32 v131, 8, v111
	v_add_u32_e32 v132, 9, v111
	v_fma_f32 v134, 0, v2, v133
	v_fmamk_f32 v135, v7, 0x3fb8aa3b, v133
	v_fma_f32 v136, 2.0, v2, v133
	v_fmac_f32_e32 v133, 0x40400000, v2
	v_cmp_lt_i32_e64 s[56:57], 6, v111
	v_fma_f32 v138, 0, v2, v137
	v_fmamk_f32 v139, v7, 0x3fb8aa3b, v137
	v_fma_f32 v140, 2.0, v2, v137
	v_fmac_f32_e32 v137, 0x40400000, v2
	v_cmp_gt_u32_e64 s[46:47], s8, v3
	v_cmp_lt_i32_e64 s[66:67], 5, v111
	v_fma_f32 v142, 0, v2, v141
	v_fmamk_f32 v143, v7, 0x3fb8aa3b, v141
	v_fma_f32 v144, 2.0, v2, v141
	v_fmac_f32_e32 v141, 0x40400000, v2
	v_cmp_lt_i32_e64 s[68:69], 4, v111
	v_fma_f32 v146, 0, v2, v145
	v_fmamk_f32 v147, v7, 0x3fb8aa3b, v145
	v_fma_f32 v148, 2.0, v2, v145
	v_fmac_f32_e32 v145, 0x40400000, v2
	v_cmp_lt_i32_e64 s[70:71], 3, v111
	v_fma_f32 v150, 0, v2, v149
	v_fmamk_f32 v151, v7, 0x3fb8aa3b, v149
	v_fma_f32 v152, 2.0, v2, v149
	v_fmac_f32_e32 v149, 0x40400000, v2
	v_cmp_lt_i32_e64 s[72:73], 2, v111
	v_fma_f32 v154, 0, v2, v153
	v_fmamk_f32 v155, v7, 0x3fb8aa3b, v153
	v_fma_f32 v156, 2.0, v2, v153
	v_fmac_f32_e32 v153, 0x40400000, v2
	v_cmp_lt_i32_e64 s[74:75], 1, v5
	v_fma_f32 v158, 0, v2, v157
	v_fmamk_f32 v159, v7, 0x3fb8aa3b, v157
	v_fma_f32 v160, 2.0, v2, v157
	v_fmac_f32_e32 v157, 0x40400000, v2
	v_fma_f32 v162, 0, v2, v161
	v_fmamk_f32 v167, v7, 0x3fb8aa3b, v161
	v_fma_f32 v168, 2.0, v2, v161
	v_fmac_f32_e32 v161, 0x40400000, v2
	v_cmp_lt_i32_e64 s[76:77], -1, v5
	v_fma_f32 v170, 0, v2, v169
	v_fmamk_f32 v171, v7, 0x3fb8aa3b, v169
	v_cmp_gt_u32_e64 s[40:41], s8, v6
	v_fma_f32 v172, 2.0, v2, v169
	v_fmac_f32_e32 v169, 0x40400000, v2
	v_fma_f32 v174, 0, v2, v173
	v_fmamk_f32 v175, v7, 0x3fb8aa3b, v173
	v_fma_f32 v176, 2.0, v2, v173
	v_cmp_gt_u32_e64 s[92:93], s8, v0
	v_fmac_f32_e32 v173, 0x40400000, v2
	v_or_b32_e32 v177, v8, v13
	v_lshlrev_b32_e32 v0, 1, v4
	s_lshl_b32 s38, s4, 2
	v_readfirstlane_b32 s100, v220
	s_nop 3
	s_lshr_b32 s100, s100, 6
	s_cmp_ge_u32 s100, 4
	s_cbranch_scc0 .Lattn_prio_done
	s_setprio 1
.Lattn_prio_done:
	s_branch .LBB0_670

.LBB0_736:
	s_setprio 0
	v_readlane_b32 s72, v254, 50
	v_readlane_b32 s70, v253, 37
	v_readlane_b32 s76, v253, 39
	v_readlane_b32 s90, v253, 41
	v_readlane_b32 s92, v253, 43
	v_readlane_b32 s62, v255, 4
	v_readlane_b32 s94, v255, 2
	s_mov_b64 s[8:9], 0
	v_readlane_b32 s73, v254, 51
	v_readlane_b32 s74, v254, 52
	v_readlane_b32 s75, v254, 53
	v_readlane_b32 s71, v253, 38
	v_readlane_b32 s77, v253, 40
	v_readlane_b32 s91, v253, 42
	v_readlane_b32 s93, v253, 44
	v_readlane_b32 s63, v255, 5
	v_readlane_b32 s95, v255, 3
